# stagger only hgrn_s1 (4 groups x s_sleep 60), s3 stagger removed
# baseline (speedup 1.0000x reference)
; #define LAS __attribute__((address_space(3)))
; #define PHASE_IDS() const int tid = fresh_tid(), lane = tid & 63, wave = __builtin_amdgcn_readfirstlane(tid >> 6); (void)lane; (void)wave
; #define SEAM(k) do { if (IN(k) && IN((k) + 1)) xcd_barrier(bar); } while (0)
; __device__ __forceinline__ void hgrn_s1(Frame& F) {
;     LAS unsigned char* lds = F.lds;
;     PHASE_IDS();
;     const int k = tid >> 2, tq = tid & 3, w = wave, fr = lane & 15, fq = lane >> 4;
;     const int kr = (k & ~31) + invperm32(k & 31);
;     const int lq = lane & ~3;
;     u32x4 rlf[2], rlb[2], raf[2], rab[2];
;     ...
;     for (int sg = F.bid; sg < NSEG; sg += F.G) {
;         const int bh = sg >> 4, seg = sg & 15;
; __global__ void __launch_bounds__(512) mk_fwd(Args args) {
;     ...
;     SEAM(1);
;     if (IN(2)) { hgrn_s1(F); __syncthreads(); sgu_phase(F); }
.LBB0_326:
	s_cmp_lt_i32 s70, 3
	s_cselect_b64 s[0:1], -1, 0
	s_and_b64 s[0:1], s[0:1], s[4:5]
	s_andn2_b64 vcc, exec, s[0:1]
	s_cbranch_vccnz .LBB0_360
	v_mov_b32_e32 v0, v254
	s_cmpk_lt_i32 s2, 0x100
	s_waitcnt lgkmcnt(0)
	s_cselect_b64 s[14:15], -1, 0
	s_cmpk_gt_i32 s2, 0xff
	v_readfirstlane_b32 s3, v0
	s_cbranch_scc1 .LBB0_347
	s_bfe_u32 s101, s2, 0x20003
	s_cmp_lt_u32 s101, 1
	s_cbranch_scc1 .Lstg_s1
	s_sleep 60
	s_cmp_lt_u32 s101, 2
	s_cbranch_scc1 .Lstg_s1
	s_sleep 60
	s_cmp_lt_u32 s101, 3
	s_cbranch_scc1 .Lstg_s1
	s_sleep 60

; #define LAS __attribute__((address_space(3)))
; #define PHASE_IDS() const int tid = fresh_tid(), lane = tid & 63, wave = __builtin_amdgcn_readfirstlane(tid >> 6); (void)lane; (void)wave
; __device__ __forceinline__ void hgrn_s3(Frame& F) {
;     LAS unsigned char* lds = F.lds;
;     PHASE_IDS();
;     const int k = tid >> 2, tq = tid & 3, w = wave, fr = lane & 15, fq = lane >> 4;
;     const int tb = w & 3, half = w >> 2, lq = lane & ~3;
;     LAS float* RSX = (LAS float*)(lds + H_RSX);
;     const int NL = F.bid < NSEG ? ((NSEG - F.bid + F.G - 1) / F.G) * NSEGC : 0;
;     u32x4 rq[2], rlf[2], rlb[2], rv[2], rsb[4], rcb[4]; f32x4 dcb[2];
;     f32x4 Rf[4][2];
;     const int kr = (k & ~31) + invperm32(k & 31), rrw = ((16 * w + fr) & ~31) + invperm32((16 * w + fr) & 31);
;     ...
;     const int pc8 = tid & 15;
;     ...
;     if (NL > 0) { S3_LOAD(0); S3_LOADS(0); }
; __global__ void __launch_bounds__(512) mk_fwd(Args args) {
;     ...
;     if (IN(4)) { hgrn_s3(F); }
.LBB0_476:
	s_cmp_lt_i32 s3, 1
	s_cbranch_scc1 .LBB0_493
	s_ashr_i32 s7, s8, 2
	v_bfi_b32 v68, -16, s7, v65
	s_and_b32 s4, s7, 0xffffffe0
	v_lshrrev_b32_e32 v0, 1, v68
	v_and_or_b32 v0, v0, 12, s4
	s_lshl_b32 s4, s2, 4
	s_ashr_i32 s6, s8, 8
	s_and_b32 s9, s4, 0xf0
	s_add_u32 s78, s68, 0x8500000
	s_addc_u32 s79, s69, 0
	s_lshl_b32 s4, s2, 1
	s_and_b32 s4, s4, 0xffffff00
	s_or_b32 s4, s4, s9
	s_mul_hi_i32 s5, s4, 0xe0000
	s_mul_i32 s4, s4, 0xe0000
	s_add_u32 s4, s78, s4
	s_addc_u32 s5, s79, s5
	s_lshl_b32 s10, s2, 10
	v_ashrrev_i32_e32 v73, 2, v65
	v_lshlrev_b32_e32 v1, 2, v65
	s_and_b32 s10, s10, 0x1c000
	v_and_b32_e32 v75, 3, v65
	v_and_b32_e32 v1, 16, v1
	v_lshrrev_b32_e32 v2, 1, v73
	s_add_u32 s4, s4, s10
	v_lshlrev_b32_e32 v152, 6, v73
	v_or3_b32 v74, v0, v1, v75
	v_and_b32_e32 v0, 0xfffffe3, v73
	v_and_b32_e32 v1, 16, v65
	v_and_b32_e32 v2, 12, v2
	s_addc_u32 s5, s5, 0
	v_ashrrev_i32_e32 v153, 31, v152
	v_or3_b32 v78, v1, v0, v2
	v_lshl_add_u64 v[0:1], v[152:153], 1, s[4:5]
	v_mov_b32_e32 v155, 0
	v_lshlrev_b32_e32 v154, 5, v75
	v_lshl_add_u64 v[0:1], v[0:1], 0, v[154:155]
	s_mov_b32 s80, 0x20000
	v_add_co_u32_e32 v6, vcc, s80, v0
	s_waitcnt lgkmcnt(0)
	s_mov_b64 s[52:53], 0x20000
	s_mov_b64 s[54:55], 0x40000
	s_add_u32 s4, s4, 0x60000
	v_lshlrev_b32_e32 v156, 3, v65
	v_addc_co_u32_e32 v7, vcc, 0, v1, vcc
	s_mov_b32 s10, 0x40000
	v_lshl_add_u64 v[2:3], v[0:1], 0, s[52:53]
	v_lshl_add_u64 v[4:5], v[0:1], 0, s[54:55]
	s_addc_u32 s5, s5, 0
	global_load_dwordx4 v[120:123], v[0:1], off offset:16
	global_load_dwordx4 v[124:127], v[0:1], off
	v_add_co_u32_e32 v0, vcc, s10, v0
	v_ashrrev_i32_e32 v157, 31, v156
	v_add_u32_e32 v158, 0x1000, v156
	v_addc_co_u32_e32 v1, vcc, 0, v1, vcc
	v_lshlrev_b64 v[66:67], 1, v[156:157]
	v_ashrrev_i32_e32 v159, 31, v158
	s_add_u32 s58, s68, 0x2c500000
	global_load_dwordx4 v[140:143], v[6:7], off
	global_load_dwordx4 v[132:135], v[0:1], off
	v_lshl_add_u64 v[0:1], s[4:5], 0, v[66:67]
	global_load_dwordx4 v[136:139], v[2:3], off offset:16
	global_load_dwordx4 v[128:131], v[4:5], off offset:16
	v_lshl_add_u64 v[2:3], v[158:159], 1, s[4:5]
	s_addc_u32 s59, s69, 0
	s_ashr_i32 s4, s2, 3
	s_or_b32 s12, s4, 1
	s_lshl_b32 s4, s12, 8
	s_or_b32 s4, s4, s9
	s_ashr_i32 s5, s4, 31
	s_lshl_b64 s[10:11], s[4:5], 15
	s_add_u32 s10, s58, s10
	s_addc_u32 s11, s59, s11
	v_lshl_add_u64 v[16:17], s[10:11], 0, v[66:67]
	s_movk_i32 s81, 0x2000
	v_add_co_u32_e32 v18, vcc, s81, v16
	s_movk_i32 s9, 0x4000
	s_nop 0
	v_addc_co_u32_e32 v19, vcc, 0, v17, vcc
	s_add_u32 s62, s68, 0x8100000
	v_add_co_u32_e32 v24, vcc, s9, v16
	s_addc_u32 s63, s69, 0
	s_lshl_b64 s[4:5], s[4:5], 9
	v_addc_co_u32_e32 v25, vcc, 0, v17, vcc
	s_movk_i32 s10, 0x6000
	s_add_u32 s4, s62, s4
	v_and_b32_e32 v76, 15, v65
	v_add_co_u32_e32 v26, vcc, s10, v16
	s_addc_u32 s5, s63, s5
	s_nop 0
	v_addc_co_u32_e32 v27, vcc, 0, v17, vcc
	v_lshlrev_b32_e32 v70, 5, v76
	s_add_u32 s76, s68, 0x3d500000
	global_load_dwordx4 v[8:11], v[0:1], off
	global_load_dwordx4 v[12:15], v[2:3], off
	s_nop 0
	global_load_dwordx4 v[0:3], v[16:17], off
	global_load_dwordx4 v[4:7], v[18:19], off
	s_nop 0
	global_load_dwordx4 v[16:19], v[24:25], off
	global_load_dwordx4 v[20:23], v[26:27], off
	s_nop 0
	global_load_dwordx4 v[24:27], v70, s[4:5] offset:16
	global_load_dwordx4 v[28:31], v70, s[4:5]
	s_addc_u32 s77, s69, 0
	s_lshl_b32 s4, s12, 4
	s_and_b32 s5, s2, 15
	s_or_b32 s4, s4, s5
	s_ashr_i32 s5, s4, 31
	s_lshl_b64 s[4:5], s[4:5], 15
	s_add_u32 s4, s76, s4
	s_addc_u32 s5, s77, s5
	v_lshl_add_u64 v[40:41], s[4:5], 0, v[66:67]
	v_add_co_u32_e32 v42, vcc, s81, v40
	s_lshl_b32 s56, s6, 6
	s_nop 0
	v_addc_co_u32_e32 v43, vcc, 0, v41, vcc
	global_load_dwordx4 v[32:35], v[40:41], off
	global_load_dwordx4 v[36:39], v[42:43], off
	v_add_co_u32_e32 v42, vcc, s9, v40
	s_ashr_i32 s57, s56, 31
	s_nop 0
	v_addc_co_u32_e32 v43, vcc, 0, v41, vcc
	s_lshl_b64 s[4:5], s[56:57], 2
	v_bfe_u32 v77, v65, 4, 2
	v_add_co_u32_e32 v40, vcc, s10, v40
	s_add_u32 s4, s60, s4
	s_nop 0
	v_addc_co_u32_e32 v41, vcc, 0, v41, vcc
	s_addc_u32 s5, s61, s5
	v_lshlrev_b32_e32 v163, 5, v77
	global_load_dwordx4 v[56:59], v[42:43], off
	global_load_dwordx4 v[60:63], v[40:41], off
	s_nop 0
	global_load_dwordx4 v[40:43], v163, s[4:5] offset:128
	global_load_dwordx4 v[44:47], v163, s[4:5] offset:144
	global_load_dwordx4 v[48:51], v163, s[4:5]
	global_load_dwordx4 v[52:55], v163, s[4:5] offset:16
	v_and_b32_e32 v84, -4, v65
	s_add_i32 s9, 0, 0x25e00
	s_lshl_b32 s6, s6, 5
	v_add_u32_e32 v178, s9, v84
	v_and_or_b32 v162, s7, 48, v76
	v_or_b32_e32 v86, s6, v76
	v_lshl_or_b32 v88, v77, 2, s6
	s_add_i32 s6, 0, 0x1e000
	s_and_b32 s8, s8, 0xffffff00
	s_add_i32 s9, 0, 0x21400
	v_lshlrev_b32_e32 v72, 3, v77
	v_lshlrev_b32_e32 v160, 4, v77
	v_mov_b32_e32 v89, s6
	v_cmp_eq_u32_e64 s[6:7], 0, v77
	s_add_i32 s8, s9, s8
	v_lshlrev_b32_e32 v77, 2, v162
	v_add_u32_e32 v181, s8, v77
	v_add_u32_e32 v182, s9, v77
	v_ashrrev_i32_e32 v77, 3, v65
	v_lshlrev_b32_e32 v90, 2, v77
	v_lshrrev_b32_e32 v91, 1, v77
	v_and_b32_e32 v90, 16, v90
	v_and_b32_e32 v91, 12, v91
	v_and_b32_e32 v77, 0xfffffe3, v77
	v_or3_b32 v77, v77, v91, v90
	v_add_u32_e32 v90, 0x200, v65
	v_ashrrev_i32_e32 v91, 3, v90
	v_lshlrev_b32_e32 v92, 2, v91
	v_lshrrev_b32_e32 v93, 1, v91
	v_and_b32_e32 v92, 16, v92
; #define LAS __attribute__((address_space(3)))
; #define F_onorm_g F_IN(6)
; __device__ __forceinline__ void hgrn_s3(Frame& F) {
;     ...
;     const int k = tid >> 2, tq = tid & 3, w = wave, fr = lane & 15, fq = lane >> 4;
;     const int tb = w & 3, half = w >> 2, lq = lane & ~3;
;     LAS float* RSX = (LAS float*)(lds + H_RSX);
;     const int NL = F.bid < NSEG ? ((NSEG - F.bid + F.G - 1) / F.G) * NSEGC : 0;
;     u32x4 rq[2], rlf[2], rlb[2], rv[2], rsb[4], rcb[4]; f32x4 dcb[2];
;     f32x4 Rf[4][2];
;     const int kr = (k & ~31) + invperm32(k & 31), rrw = ((16 * w + fr) & ~31) + invperm32((16 * w + fr) & 31);
;     ...
;     const int pc8 = tid & 15;
;     ...
;     if (NL > 0) { S3_LOAD(0); S3_LOADS(0); }
;     f32x4 ogv[2][2];
; #pragma unroll
;     for (int i = 0; i < 2; ++i) { ogv[i][0] = *(const f32x4*)(F_onorm_g + 64 * half + 32 * i + 8 * fq); ogv[i][1] = *(const f32x4*)(F_onorm_g + 64 * half + 32 * i + 8 * fq + 4); }
;     u32x4 po[2]; bf16_t* pop = nullptr;
;     ...
;             const int t = 16 * tb + fr;
; #pragma unroll
;             for (int i = 0; i < 2; ++i) { const int s0 = 16 * (2 * half + i) + 4 * fq; float pv[4];
; #pragma unroll
;                 for (int j = 0; j < 4; ++j) { const int s_ = s0 + j; pv[j] = (s_ <= t ? pf[i][j] : 0.f) + (s_ >= t ? pb[i][j] : 0.f); }
	v_and_b32_e32 v93, 12, v93
	v_and_b32_e32 v91, 0xfffffe3, v91
	v_mbcnt_lo_u32_b32 v81, -1, 0
	v_or3_b32 v91, v91, v93, v92
	v_or_b32_e32 v93, 2, v88
	v_mbcnt_hi_u32_b32 v81, -1, v81
	s_movk_i32 s47, 0x90
	s_movk_i32 s60, 0x110
	v_cmp_gt_i32_e64 s[22:23], v93, v162
	v_cmp_lt_i32_e64 s[26:27], v93, v162
	v_or_b32_e32 v93, 17, v88
	v_lshlrev_b32_e32 v64, 4, v75
	v_lshlrev_b32_e32 v79, 4, v65
	s_add_i32 s46, 0, 0x19800
	v_and_b32_e32 v82, 64, v81
	s_add_i32 s50, 0, 0x21600
	v_cmp_eq_u32_e64 s[4:5], 0, v75
	v_mul_lo_u32 v84, v74, s60
	v_lshlrev_b32_e32 v73, 1, v73
	v_or_b32_e32 v87, s56, v76
	v_mul_lo_u32 v74, v74, s47
	v_cmp_lt_u32_e64 s[8:9], 1, v75
	v_cmp_gt_u32_e64 s[10:11], 2, v75
	v_cmp_eq_u32_e64 s[12:13], 3, v75
	v_mul_u32_u24_e32 v75, 0x1100, v75
	v_or_b32_e32 v92, 1, v88
	v_cmp_gt_i32_e64 s[28:29], v93, v162
	v_cmp_lt_i32_e64 s[34:35], v93, v162
	v_or_b32_e32 v93, 19, v88
	v_and_or_b32 v83, v65, 60, v82
	s_add_i32 s14, 0, 0x11000
	v_mad_u32_u24 v179, v162, s47, v89
	v_add_u32_e32 v89, s46, v74
	v_and_b32_e32 v74, 0xf0, v79
	v_add3_u32 v187, 0, v73, v75
	v_mul_lo_u32 v73, v87, s60
	v_cmp_lt_i32_e64 s[18:19], v92, v162
	v_or_b32_e32 v92, 3, v88
	v_cmp_gt_i32_e64 s[38:39], v93, v162
	v_cmp_lt_i32_e64 s[42:43], v93, v162
	v_mov_b32_e32 v93, s50
	v_and_b32_e32 v80, 0x70, v79
	v_add_u32_e32 v84, s14, v84
	v_add_u32_e32 v79, s14, v74
	v_lshlrev_b32_e32 v183, 2, v83
	v_mul_lo_u32 v83, v86, s60
	v_add_u32_e32 v86, s14, v160
	v_add_u32_e32 v188, s14, v73
	v_cmp_gt_i32_e64 s[14:15], v88, v162
	v_cmp_lt_i32_e64 s[16:17], v88, v162
	v_cmp_gt_i32_e64 s[20:21], v92, v162
	v_cmp_lt_i32_e64 s[24:25], v92, v162
	v_lshlrev_b32_e32 v92, 1, v88
	v_or_b32_e32 v94, 16, v88
	v_or_b32_e32 v88, 18, v88
	v_mad_u32_u24 v76, v76, s47, v93
	v_ashrrev_i32_e32 v93, 4, v65
	v_cmp_gt_i32_e64 s[30:31], v94, v162
	v_cmp_lt_i32_e64 s[36:37], v94, v162
	v_cmp_gt_i32_e64 s[40:41], v88, v162
	v_cmp_lt_i32_e64 s[44:45], v88, v162
	v_lshlrev_b32_e32 v88, 1, v94
	v_lshlrev_b32_e32 v94, 2, v93
	v_lshrrev_b32_e32 v95, 1, v93
	v_and_b32_e32 v94, 16, v94
	v_and_b32_e32 v95, 12, v95
	v_and_b32_e32 v93, 0xfffffe3, v93
	v_ashrrev_i32_e32 v90, 4, v90
	v_or3_b32 v93, v93, v95, v94
	v_lshlrev_b32_e32 v94, 2, v90
	v_lshrrev_b32_e32 v95, 1, v90
	v_and_b32_e32 v94, 16, v94
	v_and_b32_e32 v95, 12, v95
	v_and_b32_e32 v90, 0xfffffe3, v90
	v_or3_b32 v90, v90, v95, v94
	v_add_u32_e32 v94, 0x400, v65
	v_ashrrev_i32_e32 v94, 4, v94
	v_lshlrev_b32_e32 v95, 2, v94
	v_lshrrev_b32_e32 v96, 1, v94
	v_add_u32_e32 v65, 0x600, v65
	v_xor_b32_e32 v99, 16, v81
	v_add_u32_e32 v82, 64, v82
	v_and_b32_e32 v95, 16, v95
	v_and_b32_e32 v96, 12, v96
	v_and_b32_e32 v94, 0xfffffe3, v94
	v_ashrrev_i32_e32 v65, 4, v65
	v_cmp_lt_i32_e32 vcc, v99, v82
	v_or3_b32 v94, v94, v96, v95
	v_lshlrev_b32_e32 v95, 2, v65
	v_lshrrev_b32_e32 v96, 1, v65
	v_cndmask_b32_e32 v99, v81, v99, vcc
	v_ashrrev_i32_e32 v69, 31, v68
	v_and_b32_e32 v95, 16, v95
	v_and_b32_e32 v96, 12, v96
	v_and_b32_e32 v65, 0xfffffe3, v65
	v_mul_lo_u32 v87, v87, s47
	v_lshlrev_b32_e32 v195, 2, v99
	v_xor_b32_e32 v99, 32, v81
	v_lshlrev_b64 v[68:69], 8, v[68:69]
	v_mul_lo_u32 v78, v78, s47
	v_or3_b32 v65, v65, v96, v95
	v_add_u32_e32 v194, s46, v87
	v_cmp_lt_i32_e32 vcc, v99, v82
	v_mov_b32_e32 v71, v155
	v_add_u32_e32 v80, s46, v80
	v_add_u32_e32 v78, s50, v78
	v_mad_u32_u24 v85, v162, s60, 0
	v_or_b32_e32 v180, 64, v160
	v_lshlrev_b32_e32 v74, 7, v162
	v_mul_lo_u32 v77, v77, s47
	v_mul_lo_u32 v91, v91, s47
	v_add_u32_e32 v75, 0, v160
	v_mul_lo_u32 v93, v93, s60
	v_mul_lo_u32 v90, v90, s60
	v_mul_lo_u32 v94, v94, s60
	v_mul_lo_u32 v65, v65, s60
	v_add_u32_e32 v95, s46, v160
	v_add_u32_e32 v96, 0x900, v194
	v_add_u32_e32 v97, 0x1200, v194
	v_add_u32_e32 v98, 0x1b00, v194
	v_cndmask_b32_e32 v81, v81, v99, vcc
	v_lshl_add_u64 v[68:69], s[76:77], 0, v[68:69]
	v_mov_b32_e32 v161, v155
	v_lshl_add_u64 v[166:167], s[58:59], 0, v[66:67]
	s_add_u32 s58, s68, 0x24500000
	s_mov_b32 s51, 0
	v_or_b32_e32 v184, 4, v183
	v_or_b32_e32 v185, 8, v183
	v_or_b32_e32 v186, 12, v183
	v_add_u32_e32 v189, 0x1100, v188
	v_add_u32_e32 v190, 0x2200, v188
	v_add_u32_e32 v191, 0x3300, v188
	v_or_b32_e32 v192, 0x80, v160
	v_or_b32_e32 v193, 0xc0, v160
	v_lshlrev_b32_e32 v196, 2, v81
	v_lshl_add_u64 v[164:165], v[68:69], 0, v[160:161]
	v_lshl_add_u64 v[168:169], s[62:63], 0, v[70:71]
	v_lshl_add_u64 v[170:171], s[76:77], 0, v[66:67]
	s_addc_u32 s59, s69, 0
	v_mov_b64_e32 v[176:177], 0
	v_add_u32_e32 v161, v80, v77
	v_add_u32_e32 v197, v80, v91
	v_lshlrev_b32_e32 v172, 1, v64
	s_mov_b32 s83, 0x3fb8aa3b
	v_add_u32_e32 v198, v78, v154
	v_add_u32_e32 v199, v84, v160
	v_add_u32_e32 v200, v75, v83
	v_add_u32_e32 v201, v179, v92
	v_add_u32_e32 v203, v179, v88
	v_add_u32_e32 v204, v89, v160
	v_add_u32_e32 v205, v76, v160
	v_add_u32_e32 v206, v79, v93
	v_add_u32_e32 v207, v79, v90
	v_add_u32_e32 v208, v79, v94
	v_add_u32_e32 v209, v79, v65
	v_lshlrev_b32_e32 v174, 1, v74
	v_lshlrev_b32_e32 v154, 1, v72
	s_mov_b64 s[60:61], 0x8580000
	s_mov_b32 s84, 0x8580000
	v_add_u32_e32 v210, v95, v87
	v_add_u32_e32 v211, v96, v180
	v_add_u32_e32 v212, v97, v180
	v_add_u32_e32 v213, v98, v180
	v_mov_b32_e32 v214, 0x358637bd
	v_add_u32_e32 v215, v85, v160
	v_add_u32_e32 v216, v86, v73
	s_mov_b32 s85, 0
	s_cmp_eq_u32 s85, 0
	s_cbranch_scc1 .LBB0_479
